# grid barrier: L1 invalidate issued early (before the spin / together with the L2 write-back) instead of after the release is observed, on top of v26
# baseline (speedup 1.0000x reference)
.LBB0_66:
	s_or_b64 exec, exec, s[6:7]
	v_cvt_f32_u32_e32 v5, v3
	s_waitcnt vmcnt(0)
	v_readfirstlane_b32 s4, v4
	v_sub_u32_e32 v4, 0, v3
	v_rcp_iflag_f32_e32 v5, v5
	v_add_u32_e32 v6, s4, v2
	v_mul_f32_e32 v5, 0x4f7ffffe, v5
	v_cvt_u32_f32_e32 v5, v5
	v_mul_lo_u32 v2, v4, v5
	v_mul_hi_u32 v2, v5, v2
	v_add_u32_e32 v2, v5, v2
	v_mul_hi_u32 v2, v6, v2
	v_mul_lo_u32 v4, v2, v3
	v_sub_u32_e32 v4, v6, v4
	v_add_u32_e32 v5, 1, v2
	v_cmp_ge_u32_e32 vcc, v4, v3
	s_nop 1
	v_cndmask_b32_e32 v2, v2, v5, vcc
	v_sub_u32_e32 v5, v4, v3
	v_cndmask_b32_e32 v4, v4, v5, vcc
	v_add_u32_e32 v5, 1, v2
	v_cmp_ge_u32_e32 vcc, v4, v3
	v_add_u32_e32 v4, 1, v6
	s_nop 0
	v_cndmask_b32_e32 v2, v2, v5, vcc
	v_mul_lo_u32 v5, v3, v2
	v_add_u32_e32 v3, v5, v3
	v_cmp_ne_u32_e32 vcc, v4, v3
	s_and_saveexec_b64 s[4:5], vcc
	s_xor_b64 s[4:5], exec, s[4:5]
	s_cbranch_execz .LBB0_80
	buffer_inv sc1
	s_waitcnt lgkmcnt(0)
	v_mov_b32_e32 v1, 0x2000
	global_load_dword v1, v1, s[2:3] offset:1024 sc1
	s_add_u32 s10, s2, 0x2400
	s_addc_u32 s11, s3, 0
	s_waitcnt vmcnt(0)
	v_cmp_eq_u32_e32 vcc, v1, v2
	s_and_saveexec_b64 s[6:7], vcc
	s_cbranch_execz .LBB0_79
	s_add_u32 s8, s74, 0x4200
	s_addc_u32 s9, s75, 0
	s_mov_b32 s13, 1
	s_mov_b64 s[16:17], 0
	v_mov_b32_e32 v1, 0
	s_branch .LBB0_70

.LBB0_79:
	s_or_b64 exec, exec, s[6:7]
	s_waitcnt vmcnt(0)
	s_waitcnt vmcnt(0)
.LBB0_80:
	s_andn2_saveexec_b64 s[4:5], s[4:5]
	s_cbranch_execz .LBB0_100
	s_mov_b64 s[4:5], exec
	buffer_wbl2 sc1
	buffer_inv sc1
	s_waitcnt lgkmcnt(0)
	s_waitcnt vmcnt(0)
	v_mbcnt_lo_u32_b32 v2, s4, 0
	v_mbcnt_hi_u32_b32 v2, s5, v2
	v_cmp_eq_u32_e32 vcc, 0, v2
	s_and_saveexec_b64 s[6:7], vcc
	s_cbranch_execz .LBB0_83
	s_bcnt1_i32_b64 s4, s[4:5]
	v_mov_b32_e32 v3, 0x7000
	v_mov_b32_e32 v4, s4
	global_atomic_add v3, v3, v4, s[74:75] offset:1024 sc0

.LBB0_97:
	s_or_b64 exec, exec, s[4:5]
	s_mov_b64 s[4:5], exec
	v_mbcnt_lo_u32_b32 v1, s4, 0
	v_mbcnt_hi_u32_b32 v1, s5, v1
	v_cmp_eq_u32_e32 vcc, 0, v1
	s_waitcnt vmcnt(0)
	s_and_saveexec_b64 s[6:7], vcc
	s_cbranch_execz .LBB0_99
	s_bcnt1_i32_b64 s4, s[4:5]
	v_mov_b32_e32 v1, 0x2000
	v_mov_b32_e32 v2, s4
	global_atomic_add v1, v2, s[2:3] offset:1024

.LBB0_179:
	s_or_b64 exec, exec, s[6:7]
	v_cvt_f32_u32_e32 v5, v3
	s_waitcnt vmcnt(0)
	v_readfirstlane_b32 s4, v4
	v_sub_u32_e32 v4, 0, v3
	v_rcp_iflag_f32_e32 v5, v5
	v_add_u32_e32 v6, s4, v2
	v_mul_f32_e32 v5, 0x4f7ffffe, v5
	v_cvt_u32_f32_e32 v5, v5
	v_mul_lo_u32 v2, v4, v5
	v_mul_hi_u32 v2, v5, v2
	v_add_u32_e32 v2, v5, v2
	v_mul_hi_u32 v2, v6, v2
	v_mul_lo_u32 v4, v2, v3
	v_sub_u32_e32 v4, v6, v4
	v_add_u32_e32 v5, 1, v2
	v_cmp_ge_u32_e32 vcc, v4, v3
	s_nop 1
	v_cndmask_b32_e32 v2, v2, v5, vcc
	v_sub_u32_e32 v5, v4, v3
	v_cndmask_b32_e32 v4, v4, v5, vcc
	v_add_u32_e32 v5, 1, v2
	v_cmp_ge_u32_e32 vcc, v4, v3
	v_add_u32_e32 v4, 1, v6
	s_nop 0
	v_cndmask_b32_e32 v2, v2, v5, vcc
	v_mul_lo_u32 v5, v3, v2
	v_add_u32_e32 v3, v5, v3
	v_cmp_ne_u32_e32 vcc, v4, v3
	s_and_saveexec_b64 s[4:5], vcc
	s_xor_b64 s[4:5], exec, s[4:5]
	s_cbranch_execz .LBB0_193
	buffer_inv sc1
	s_waitcnt lgkmcnt(0)
	v_mov_b32_e32 v1, 0x2000
	global_load_dword v1, v1, s[2:3] offset:1024 sc1
	s_add_u32 s10, s2, 0x2400
	s_addc_u32 s11, s3, 0
	s_waitcnt vmcnt(0)
	v_cmp_eq_u32_e32 vcc, v1, v2
	s_and_saveexec_b64 s[6:7], vcc
	s_cbranch_execz .LBB0_192
	s_add_u32 s8, s74, 0x4200
	s_addc_u32 s9, s75, 0
	s_mov_b32 s12, 1
	s_mov_b64 s[16:17], 0
	v_mov_b32_e32 v1, 0
	s_branch .LBB0_183

.LBB0_997:
	s_or_b64 exec, exec, s[6:7]
	v_cvt_f32_u32_e32 v5, v3
	s_waitcnt vmcnt(0)
	v_readfirstlane_b32 s4, v4
	v_sub_u32_e32 v4, 0, v3
	v_rcp_iflag_f32_e32 v5, v5
	v_add_u32_e32 v6, s4, v2
	v_mul_f32_e32 v5, 0x4f7ffffe, v5
	v_cvt_u32_f32_e32 v5, v5
	v_mul_lo_u32 v2, v4, v5
	v_mul_hi_u32 v2, v5, v2
	v_add_u32_e32 v2, v5, v2
	v_mul_hi_u32 v2, v6, v2
	v_mul_lo_u32 v4, v2, v3
	v_sub_u32_e32 v4, v6, v4
	v_add_u32_e32 v5, 1, v2
	v_cmp_ge_u32_e32 vcc, v4, v3
	s_nop 1
	v_cndmask_b32_e32 v2, v2, v5, vcc
	v_sub_u32_e32 v5, v4, v3
	v_cndmask_b32_e32 v4, v4, v5, vcc
	v_add_u32_e32 v5, 1, v2
	v_cmp_ge_u32_e32 vcc, v4, v3
	v_add_u32_e32 v4, 1, v6
	s_nop 0
	v_cndmask_b32_e32 v2, v2, v5, vcc
	v_mul_lo_u32 v5, v3, v2
	v_add_u32_e32 v3, v5, v3
	v_cmp_ne_u32_e32 vcc, v4, v3
	s_and_saveexec_b64 s[4:5], vcc
	s_xor_b64 s[4:5], exec, s[4:5]
	s_cbranch_execz .LBB0_1011
	buffer_inv sc1
	s_waitcnt lgkmcnt(0)
	v_mov_b32_e32 v1, 0x2000
	global_load_dword v1, v1, s[2:3] offset:1024 sc1
	s_add_u32 s10, s2, 0x2400
	s_addc_u32 s11, s3, 0
	s_waitcnt vmcnt(0)
	v_cmp_eq_u32_e32 vcc, v1, v2
	s_and_saveexec_b64 s[6:7], vcc
	s_cbranch_execz .LBB0_1010
	s_add_u32 s8, s74, 0x4200
	s_addc_u32 s9, s75, 0
	s_mov_b32 s15, 1
	s_mov_b64 s[12:13], 0
	v_mov_b32_e32 v1, 0
	s_branch .LBB0_1001
